# on top of SGPR-base LDS-DMA addressing: removed the no-op s_setprio 0/1 pair between the two 16-MFMA halves of each block and the already-satisfied lgkmcnt(0) after the block's opening barrier, in all
# speedup vs baseline: 1.0068x; 1.0012x over previous
.LBB0_432:
	ds_read_b128 v[150:153], v159
	ds_read_b128 v[154:157], v159 offset:1024
	ds_read_b128 v[162:165], v159 offset:2048
	ds_read_b128 v[166:169], v159 offset:3072
	ds_read_b128 v[170:173], v160
	ds_read_b128 v[174:177], v160 offset:1024
	ds_read_b128 v[178:181], v160 offset:2048
	ds_read_b128 v[182:185], v160 offset:3072
	s_add_u32 s42, s40, 0xfff00080
	s_addc_u32 s43, s41, -1
	s_cmp_eq_u32 s74, 60
	s_cselect_b32 s45, s35, s43
	s_cselect_b32 s44, s70, s42
	s_cselect_b32 s43, s31, s73
	s_cselect_b32 s42, s71, s72
	s_add_i32 m0, s55, 0xc000
	ds_read_b128 v[186:189], v161
	ds_read_b128 v[190:193], v161 offset:1024
	ds_read_b128 v[194:197], v161 offset:2048
	ds_read_b128 v[198:201], v161 offset:3072
	ds_read_b128 v[202:205], v161 offset:4096
	ds_read_b128 v[206:209], v161 offset:5120
	ds_read_b128 v[210:213], v161 offset:6144
	ds_read_b128 v[214:217], v161 offset:7168
	global_load_lds_dwordx4 v144, s[40:41]
	s_add_i32 m0, s55, 0xe000
	s_nop 0
	global_load_lds_dwordx4 v142, s[40:41]
	s_waitcnt vmcnt(8)
	s_waitcnt lgkmcnt(0)
	s_barrier
	s_setprio 1
	v_mfma_f32_16x16x32_bf16 v[92:95], v[150:153], v[186:189], v[92:95]
	v_mfma_f32_16x16x32_bf16 v[88:91], v[162:165], v[186:189], v[88:91]
	v_mfma_f32_16x16x32_bf16 v[84:87], v[150:153], v[194:197], v[84:87]
	v_mfma_f32_16x16x32_bf16 v[80:83], v[162:165], v[194:197], v[80:83]
	v_mfma_f32_16x16x32_bf16 v[76:79], v[150:153], v[202:205], v[76:79]
	v_mfma_f32_16x16x32_bf16 v[68:71], v[162:165], v[202:205], v[68:71]
	v_mfma_f32_16x16x32_bf16 v[60:63], v[150:153], v[210:213], v[60:63]
	v_mfma_f32_16x16x32_bf16 v[56:59], v[162:165], v[210:213], v[56:59]
	v_mfma_f32_16x16x32_bf16 v[92:95], v[154:157], v[190:193], v[92:95]
	v_mfma_f32_16x16x32_bf16 v[88:91], v[166:169], v[190:193], v[88:91]
	v_mfma_f32_16x16x32_bf16 v[84:87], v[154:157], v[198:201], v[84:87]
	v_mfma_f32_16x16x32_bf16 v[80:83], v[166:169], v[198:201], v[80:83]
	v_mfma_f32_16x16x32_bf16 v[76:79], v[154:157], v[206:209], v[76:79]
	v_mfma_f32_16x16x32_bf16 v[68:71], v[166:169], v[206:209], v[68:71]
	v_mfma_f32_16x16x32_bf16 v[60:63], v[154:157], v[214:217], v[60:63]
	v_mfma_f32_16x16x32_bf16 v[56:59], v[166:169], v[214:217], v[56:59]
	v_mfma_f32_16x16x32_bf16 v[124:127], v[170:173], v[186:189], v[124:127]
	v_mfma_f32_16x16x32_bf16 v[120:123], v[178:181], v[186:189], v[120:123]
	v_mfma_f32_16x16x32_bf16 v[116:119], v[170:173], v[194:197], v[116:119]
	v_mfma_f32_16x16x32_bf16 v[112:115], v[178:181], v[194:197], v[112:115]
	v_mfma_f32_16x16x32_bf16 v[108:111], v[170:173], v[202:205], v[108:111]
	v_mfma_f32_16x16x32_bf16 v[104:107], v[178:181], v[202:205], v[104:107]
	v_mfma_f32_16x16x32_bf16 v[100:103], v[170:173], v[210:213], v[100:103]
	v_mfma_f32_16x16x32_bf16 v[96:99], v[178:181], v[210:213], v[96:99]
	v_mfma_f32_16x16x32_bf16 v[124:127], v[174:177], v[190:193], v[124:127]
	v_mfma_f32_16x16x32_bf16 v[120:123], v[182:185], v[190:193], v[120:123]
	v_mfma_f32_16x16x32_bf16 v[116:119], v[174:177], v[198:201], v[116:119]
	v_mfma_f32_16x16x32_bf16 v[112:115], v[182:185], v[198:201], v[112:115]
	v_mfma_f32_16x16x32_bf16 v[108:111], v[174:177], v[206:209], v[108:111]
	v_mfma_f32_16x16x32_bf16 v[104:107], v[182:185], v[206:209], v[104:107]
	v_mfma_f32_16x16x32_bf16 v[100:103], v[174:177], v[214:217], v[100:103]
	v_mfma_f32_16x16x32_bf16 v[96:99], v[182:185], v[214:217], v[96:99]
	s_setprio 0
	s_barrier
	s_add_u32 s98, s42, 0x80
	s_addc_u32 s99, s43, 0
	s_add_u32 s100, s44, 0x80
	s_addc_u32 s101, s45, 0
	s_add_i32 s75, s65, s53
	s_mov_b32 m0, s75
	ds_read_b128 v[186:189], v161 offset:16384
	ds_read_b128 v[190:193], v161 offset:17408
	ds_read_b128 v[194:197], v161 offset:18432
	ds_read_b128 v[198:201], v161 offset:19456
	ds_read_b128 v[202:205], v161 offset:20480
	ds_read_b128 v[206:209], v161 offset:21504
	ds_read_b128 v[210:213], v161 offset:22528
	ds_read_b128 v[214:217], v161 offset:23552
	global_load_lds_dwordx4 v132, s[42:43]
	s_add_i32 m0, s75, 0x2000
	s_add_u32 s76, s42, 0x100000
	s_addc_u32 s77, s43, 0
	s_add_i32 s75, s66, s53
	global_load_lds_dwordx4 v128, s[42:43]
	s_mov_b32 m0, s75
	s_nop 0
	global_load_lds_dwordx4 v132, s[76:77]
	s_add_i32 m0, s75, 0x2000
	s_nop 0
	global_load_lds_dwordx4 v128, s[76:77]
	s_mov_b32 m0, s55
	s_nop 0
	global_load_lds_dwordx4 v134, s[44:45]
	s_mov_b32 m0, s56
	s_nop 0
	global_load_lds_dwordx4 v130, s[44:45]
	s_waitcnt vmcnt(8)
	s_waitcnt lgkmcnt(0)
	s_barrier
	s_setprio 1
	v_mfma_f32_16x16x32_bf16 v[32:35], v[150:153], v[186:189], v[32:35]
	v_mfma_f32_16x16x32_bf16 v[28:31], v[162:165], v[186:189], v[28:31]
	v_mfma_f32_16x16x32_bf16 v[20:23], v[150:153], v[194:197], v[20:23]
	v_mfma_f32_16x16x32_bf16 v[16:19], v[162:165], v[194:197], v[16:19]
	v_mfma_f32_16x16x32_bf16 v[12:15], v[150:153], v[202:205], v[12:15]
	v_mfma_f32_16x16x32_bf16 v[8:11], v[162:165], v[202:205], v[8:11]
	v_mfma_f32_16x16x32_bf16 v[4:7], v[150:153], v[210:213], v[4:7]
	v_mfma_f32_16x16x32_bf16 v[0:3], v[162:165], v[210:213], v[0:3]
	v_mfma_f32_16x16x32_bf16 v[32:35], v[154:157], v[190:193], v[32:35]
	v_mfma_f32_16x16x32_bf16 v[28:31], v[166:169], v[190:193], v[28:31]
	v_mfma_f32_16x16x32_bf16 v[20:23], v[154:157], v[198:201], v[20:23]
	v_mfma_f32_16x16x32_bf16 v[16:19], v[166:169], v[198:201], v[16:19]
	v_mfma_f32_16x16x32_bf16 v[12:15], v[154:157], v[206:209], v[12:15]
	v_mfma_f32_16x16x32_bf16 v[8:11], v[166:169], v[206:209], v[8:11]
	v_mfma_f32_16x16x32_bf16 v[4:7], v[154:157], v[214:217], v[4:7]
	v_mfma_f32_16x16x32_bf16 v[0:3], v[166:169], v[214:217], v[0:3]
	v_mfma_f32_16x16x32_bf16 v[72:75], v[170:173], v[186:189], v[72:75]
	v_mfma_f32_16x16x32_bf16 v[64:67], v[178:181], v[186:189], v[64:67]
	v_mfma_f32_16x16x32_bf16 v[52:55], v[170:173], v[194:197], v[52:55]
	v_mfma_f32_16x16x32_bf16 v[48:51], v[178:181], v[194:197], v[48:51]
	v_mfma_f32_16x16x32_bf16 v[44:47], v[170:173], v[202:205], v[44:47]
	v_mfma_f32_16x16x32_bf16 v[40:43], v[178:181], v[202:205], v[40:43]
	v_mfma_f32_16x16x32_bf16 v[36:39], v[170:173], v[210:213], v[36:39]
	v_mfma_f32_16x16x32_bf16 v[24:27], v[178:181], v[210:213], v[24:27]
	v_mfma_f32_16x16x32_bf16 v[72:75], v[174:177], v[190:193], v[72:75]
	v_mfma_f32_16x16x32_bf16 v[64:67], v[182:185], v[190:193], v[64:67]
	v_mfma_f32_16x16x32_bf16 v[52:55], v[174:177], v[198:201], v[52:55]
	v_mfma_f32_16x16x32_bf16 v[48:51], v[182:185], v[198:201], v[48:51]
	v_mfma_f32_16x16x32_bf16 v[44:47], v[174:177], v[206:209], v[44:47]
	v_mfma_f32_16x16x32_bf16 v[40:43], v[182:185], v[206:209], v[40:43]
	v_mfma_f32_16x16x32_bf16 v[36:39], v[174:177], v[214:217], v[36:39]
	v_mfma_f32_16x16x32_bf16 v[24:27], v[182:185], v[214:217], v[24:27]
	s_setprio 0
	s_barrier
	s_add_i32 s75, 0, 0x18000
	v_add_u32_e32 v136, s75, v158
	s_add_i32 s76, 0, 0x1c000
	ds_read_b128 v[150:153], v136
	ds_read_b128 v[154:157], v136 offset:1024
	ds_read_b128 v[162:165], v136 offset:2048
	ds_read_b128 v[166:169], v136 offset:3072
	v_add_u32_e32 v136, s76, v158
	ds_read_b128 v[170:173], v136
	ds_read_b128 v[174:177], v136 offset:1024
	ds_read_b128 v[178:181], v136 offset:2048
	ds_read_b128 v[182:185], v136 offset:3072
	s_add_u32 s44, s44, 0x100000
	s_addc_u32 s45, s45, 0
	s_mov_b32 m0, s57
	ds_read_b128 v[186:189], v161 offset:32768
	ds_read_b128 v[190:193], v161 offset:33792
	ds_read_b128 v[194:197], v161 offset:34816
	ds_read_b128 v[198:201], v161 offset:35840
	ds_read_b128 v[202:205], v161 offset:36864
	ds_read_b128 v[206:209], v161 offset:37888
	ds_read_b128 v[210:213], v161 offset:38912
	ds_read_b128 v[214:217], v161 offset:39936
	global_load_lds_dwordx4 v134, s[44:45]
	s_mov_b32 m0, s58
	s_nop 0
	global_load_lds_dwordx4 v130, s[44:45]
	s_waitcnt vmcnt(8)
	s_waitcnt lgkmcnt(0)
	s_barrier
	s_setprio 1
	v_mfma_f32_16x16x32_bf16 v[92:95], v[150:153], v[186:189], v[92:95]
	v_mfma_f32_16x16x32_bf16 v[88:91], v[162:165], v[186:189], v[88:91]
	v_mfma_f32_16x16x32_bf16 v[84:87], v[150:153], v[194:197], v[84:87]
	v_mfma_f32_16x16x32_bf16 v[80:83], v[162:165], v[194:197], v[80:83]
	v_mfma_f32_16x16x32_bf16 v[76:79], v[150:153], v[202:205], v[76:79]
	v_mfma_f32_16x16x32_bf16 v[68:71], v[162:165], v[202:205], v[68:71]
	v_mfma_f32_16x16x32_bf16 v[60:63], v[150:153], v[210:213], v[60:63]
	v_mfma_f32_16x16x32_bf16 v[56:59], v[162:165], v[210:213], v[56:59]
	v_mfma_f32_16x16x32_bf16 v[92:95], v[154:157], v[190:193], v[92:95]
	v_mfma_f32_16x16x32_bf16 v[88:91], v[166:169], v[190:193], v[88:91]
	v_mfma_f32_16x16x32_bf16 v[84:87], v[154:157], v[198:201], v[84:87]
	v_mfma_f32_16x16x32_bf16 v[80:83], v[166:169], v[198:201], v[80:83]
	v_mfma_f32_16x16x32_bf16 v[76:79], v[154:157], v[206:209], v[76:79]
	v_mfma_f32_16x16x32_bf16 v[68:71], v[166:169], v[206:209], v[68:71]
	v_mfma_f32_16x16x32_bf16 v[60:63], v[154:157], v[214:217], v[60:63]
	v_mfma_f32_16x16x32_bf16 v[56:59], v[166:169], v[214:217], v[56:59]
	v_mfma_f32_16x16x32_bf16 v[124:127], v[170:173], v[186:189], v[124:127]
	v_mfma_f32_16x16x32_bf16 v[120:123], v[178:181], v[186:189], v[120:123]
	v_mfma_f32_16x16x32_bf16 v[116:119], v[170:173], v[194:197], v[116:119]
	v_mfma_f32_16x16x32_bf16 v[112:115], v[178:181], v[194:197], v[112:115]
	v_mfma_f32_16x16x32_bf16 v[108:111], v[170:173], v[202:205], v[108:111]
	v_mfma_f32_16x16x32_bf16 v[104:107], v[178:181], v[202:205], v[104:107]
	v_mfma_f32_16x16x32_bf16 v[100:103], v[170:173], v[210:213], v[100:103]
	v_mfma_f32_16x16x32_bf16 v[96:99], v[178:181], v[210:213], v[96:99]
	v_mfma_f32_16x16x32_bf16 v[124:127], v[174:177], v[190:193], v[124:127]
	v_mfma_f32_16x16x32_bf16 v[120:123], v[182:185], v[190:193], v[120:123]
	v_mfma_f32_16x16x32_bf16 v[116:119], v[174:177], v[198:201], v[116:119]
	v_mfma_f32_16x16x32_bf16 v[112:115], v[182:185], v[198:201], v[112:115]
	v_mfma_f32_16x16x32_bf16 v[108:111], v[174:177], v[206:209], v[108:111]
	v_mfma_f32_16x16x32_bf16 v[104:107], v[182:185], v[206:209], v[104:107]
	v_mfma_f32_16x16x32_bf16 v[100:103], v[174:177], v[214:217], v[100:103]
	v_mfma_f32_16x16x32_bf16 v[96:99], v[182:185], v[214:217], v[96:99]
	s_setprio 0
	s_barrier
	s_add_i32 s44, s75, s53
	s_mov_b32 m0, s44
	ds_read_b128 v[186:189], v161 offset:49152
	ds_read_b128 v[190:193], v161 offset:50176
	ds_read_b128 v[194:197], v161 offset:51200
	ds_read_b128 v[198:201], v161 offset:52224
	ds_read_b128 v[202:205], v161 offset:53248
	ds_read_b128 v[206:209], v161 offset:54272
	ds_read_b128 v[210:213], v161 offset:55296
	ds_read_b128 v[214:217], v161 offset:56320
	global_load_lds_dwordx4 v132, s[98:99]
	s_add_i32 m0, s44, 0x2000
	s_add_u32 s42, s42, 0x100080
	s_addc_u32 s43, s43, 0
	s_add_i32 s44, s76, s53
	global_load_lds_dwordx4 v128, s[98:99]
	s_mov_b32 m0, s44
	s_nop 0
	global_load_lds_dwordx4 v132, s[42:43]
	s_add_i32 m0, s44, 0x2000
	s_nop 0
	global_load_lds_dwordx4 v128, s[42:43]
	s_mov_b32 m0, s62
	s_nop 0
	global_load_lds_dwordx4 v134, s[100:101]
	s_mov_b32 m0, s63
	s_nop 0
	global_load_lds_dwordx4 v130, s[100:101]
	s_waitcnt vmcnt(8)
	s_waitcnt lgkmcnt(0)
	s_barrier
	s_setprio 1
	v_mfma_f32_16x16x32_bf16 v[32:35], v[150:153], v[186:189], v[32:35]
	v_mfma_f32_16x16x32_bf16 v[28:31], v[162:165], v[186:189], v[28:31]
	v_mfma_f32_16x16x32_bf16 v[20:23], v[150:153], v[194:197], v[20:23]
	v_mfma_f32_16x16x32_bf16 v[16:19], v[162:165], v[194:197], v[16:19]
	v_mfma_f32_16x16x32_bf16 v[12:15], v[150:153], v[202:205], v[12:15]
	v_mfma_f32_16x16x32_bf16 v[8:11], v[162:165], v[202:205], v[8:11]
	v_mfma_f32_16x16x32_bf16 v[4:7], v[150:153], v[210:213], v[4:7]
	v_mfma_f32_16x16x32_bf16 v[0:3], v[162:165], v[210:213], v[0:3]
	v_mfma_f32_16x16x32_bf16 v[32:35], v[154:157], v[190:193], v[32:35]
	v_mfma_f32_16x16x32_bf16 v[28:31], v[166:169], v[190:193], v[28:31]
	v_mfma_f32_16x16x32_bf16 v[20:23], v[154:157], v[198:201], v[20:23]
	v_mfma_f32_16x16x32_bf16 v[16:19], v[166:169], v[198:201], v[16:19]
	v_mfma_f32_16x16x32_bf16 v[12:15], v[154:157], v[206:209], v[12:15]
	v_mfma_f32_16x16x32_bf16 v[8:11], v[166:169], v[206:209], v[8:11]
	v_mfma_f32_16x16x32_bf16 v[4:7], v[154:157], v[214:217], v[4:7]
	v_mfma_f32_16x16x32_bf16 v[0:3], v[166:169], v[214:217], v[0:3]
	v_mfma_f32_16x16x32_bf16 v[72:75], v[170:173], v[186:189], v[72:75]
	v_mfma_f32_16x16x32_bf16 v[64:67], v[178:181], v[186:189], v[64:67]
	v_mfma_f32_16x16x32_bf16 v[52:55], v[170:173], v[194:197], v[52:55]
	v_mfma_f32_16x16x32_bf16 v[48:51], v[178:181], v[194:197], v[48:51]
	v_mfma_f32_16x16x32_bf16 v[44:47], v[170:173], v[202:205], v[44:47]
	v_mfma_f32_16x16x32_bf16 v[40:43], v[178:181], v[202:205], v[40:43]
	v_mfma_f32_16x16x32_bf16 v[36:39], v[170:173], v[210:213], v[36:39]
	v_mfma_f32_16x16x32_bf16 v[24:27], v[178:181], v[210:213], v[24:27]
	v_mfma_f32_16x16x32_bf16 v[72:75], v[174:177], v[190:193], v[72:75]
	v_mfma_f32_16x16x32_bf16 v[64:67], v[182:185], v[190:193], v[64:67]
	v_mfma_f32_16x16x32_bf16 v[52:55], v[174:177], v[198:201], v[52:55]
	v_mfma_f32_16x16x32_bf16 v[48:51], v[182:185], v[198:201], v[48:51]
	v_mfma_f32_16x16x32_bf16 v[44:47], v[174:177], v[206:209], v[44:47]
	v_mfma_f32_16x16x32_bf16 v[40:43], v[182:185], v[206:209], v[40:43]
	v_mfma_f32_16x16x32_bf16 v[36:39], v[174:177], v[214:217], v[36:39]
	v_mfma_f32_16x16x32_bf16 v[24:27], v[182:185], v[214:217], v[24:27]
	s_setprio 0
	s_barrier
	s_add_i32 s74, s74, 2
	s_add_u32 s72, s72, 0x100
	s_addc_u32 s73, s73, 0
	s_add_u32 s40, s40, 0x100
	s_addc_u32 s41, s41, 0
	s_cmp_gt_u32 s74, 61
	s_cbranch_scc0 .LBB0_432
	s_and_b64 vcc, exec, s[14:15]
	s_cbranch_vccz .LBB0_436
	s_barrier
	v_lshl_add_u32 v150, s12, 8, v139
	s_cmp_lg_u32 s69, 54
	s_mov_b64 s[40:41], -1
	s_cbranch_scc1 .LBB0_437

.LBB0_1612:
	ds_read_b128 v[144:147], v151
	ds_read_b128 v[156:159], v151 offset:1024
	ds_read_b128 v[160:163], v151 offset:2048
	ds_read_b128 v[164:167], v151 offset:3072
	ds_read_b128 v[168:171], v152
	ds_read_b128 v[172:175], v152 offset:1024
	ds_read_b128 v[176:179], v152 offset:2048
	ds_read_b128 v[180:183], v152 offset:3072
	s_add_u32 s34, s30, 0xfff00080
	s_addc_u32 s35, s31, -1
	s_cmp_eq_u32 s59, 60
	s_cselect_b32 s37, s25, s35
	s_cselect_b32 s36, s55, s34
	s_cselect_b32 s35, s23, s58
	s_cselect_b32 s34, s56, s57
	s_add_i32 m0, s9, 0xc000
	ds_read_b128 v[184:187], v153
	ds_read_b128 v[188:191], v153 offset:1024
	ds_read_b128 v[192:195], v153 offset:2048
	ds_read_b128 v[196:199], v153 offset:3072
	ds_read_b128 v[200:203], v153 offset:4096
	ds_read_b128 v[204:207], v153 offset:5120
	ds_read_b128 v[208:211], v153 offset:6144
	ds_read_b128 v[212:215], v153 offset:7168
	global_load_lds_dwordx4 v138, s[30:31]
	s_add_i32 m0, s9, 0xe000
	s_nop 0
	global_load_lds_dwordx4 v136, s[30:31]
	s_waitcnt vmcnt(8)
	s_waitcnt lgkmcnt(0)
	s_barrier
	s_setprio 1
	v_mfma_f32_16x16x32_bf16 v[124:127], v[144:147], v[184:187], v[124:127]
	v_mfma_f32_16x16x32_bf16 v[120:123], v[160:163], v[184:187], v[120:123]
	v_mfma_f32_16x16x32_bf16 v[108:111], v[144:147], v[192:195], v[108:111]
	v_mfma_f32_16x16x32_bf16 v[104:107], v[160:163], v[192:195], v[104:107]
	v_mfma_f32_16x16x32_bf16 v[92:95], v[144:147], v[200:203], v[92:95]
	v_mfma_f32_16x16x32_bf16 v[88:91], v[160:163], v[200:203], v[88:91]
	v_mfma_f32_16x16x32_bf16 v[76:79], v[144:147], v[208:211], v[76:79]
	v_mfma_f32_16x16x32_bf16 v[72:75], v[160:163], v[208:211], v[72:75]
	v_mfma_f32_16x16x32_bf16 v[124:127], v[156:159], v[188:191], v[124:127]
	v_mfma_f32_16x16x32_bf16 v[120:123], v[164:167], v[188:191], v[120:123]
	v_mfma_f32_16x16x32_bf16 v[108:111], v[156:159], v[196:199], v[108:111]
	v_mfma_f32_16x16x32_bf16 v[104:107], v[164:167], v[196:199], v[104:107]
	v_mfma_f32_16x16x32_bf16 v[92:95], v[156:159], v[204:207], v[92:95]
	v_mfma_f32_16x16x32_bf16 v[88:91], v[164:167], v[204:207], v[88:91]
	v_mfma_f32_16x16x32_bf16 v[76:79], v[156:159], v[212:215], v[76:79]
	v_mfma_f32_16x16x32_bf16 v[72:75], v[164:167], v[212:215], v[72:75]
	v_mfma_f32_16x16x32_bf16 v[116:119], v[168:171], v[184:187], v[116:119]
	v_mfma_f32_16x16x32_bf16 v[112:115], v[176:179], v[184:187], v[112:115]
	v_mfma_f32_16x16x32_bf16 v[100:103], v[168:171], v[192:195], v[100:103]
	v_mfma_f32_16x16x32_bf16 v[96:99], v[176:179], v[192:195], v[96:99]
	v_mfma_f32_16x16x32_bf16 v[84:87], v[168:171], v[200:203], v[84:87]
	v_mfma_f32_16x16x32_bf16 v[80:83], v[176:179], v[200:203], v[80:83]
	v_mfma_f32_16x16x32_bf16 v[68:71], v[168:171], v[208:211], v[68:71]
	v_mfma_f32_16x16x32_bf16 v[64:67], v[176:179], v[208:211], v[64:67]
	v_mfma_f32_16x16x32_bf16 v[116:119], v[172:175], v[188:191], v[116:119]
	v_mfma_f32_16x16x32_bf16 v[112:115], v[180:183], v[188:191], v[112:115]
	v_mfma_f32_16x16x32_bf16 v[100:103], v[172:175], v[196:199], v[100:103]
	v_mfma_f32_16x16x32_bf16 v[96:99], v[180:183], v[196:199], v[96:99]
	v_mfma_f32_16x16x32_bf16 v[84:87], v[172:175], v[204:207], v[84:87]
	v_mfma_f32_16x16x32_bf16 v[80:83], v[180:183], v[204:207], v[80:83]
	v_mfma_f32_16x16x32_bf16 v[68:71], v[172:175], v[212:215], v[68:71]
	v_mfma_f32_16x16x32_bf16 v[64:67], v[180:183], v[212:215], v[64:67]
	s_setprio 0
	s_barrier
	s_add_u32 s98, s34, 0x80
	s_addc_u32 s99, s35, 0
	s_add_u32 s100, s36, 0x80
	s_addc_u32 s101, s37, 0
	s_add_i32 s60, s52, s45
	s_mov_b32 m0, s60
	ds_read_b128 v[184:187], v153 offset:16384
	ds_read_b128 v[188:191], v153 offset:17408
	ds_read_b128 v[192:195], v153 offset:18432
	ds_read_b128 v[196:199], v153 offset:19456
	ds_read_b128 v[200:203], v153 offset:20480
	ds_read_b128 v[204:207], v153 offset:21504
	ds_read_b128 v[208:211], v153 offset:22528
	ds_read_b128 v[212:215], v153 offset:23552
	global_load_lds_dwordx4 v130, s[34:35]
	s_add_i32 m0, s60, 0x2000
	s_add_u32 s60, s34, 0x100000
	s_addc_u32 s61, s35, 0
	s_add_i32 s62, s53, s45
	global_load_lds_dwordx4 v134, s[34:35]
	s_mov_b32 m0, s62
	s_nop 0
	global_load_lds_dwordx4 v130, s[60:61]
	s_add_i32 m0, s62, 0x2000
	s_nop 0
	global_load_lds_dwordx4 v134, s[60:61]
	s_mov_b32 m0, s9
	s_nop 0
	global_load_lds_dwordx4 v128, s[36:37]
	s_mov_b32 m0, s46
	s_nop 0
	global_load_lds_dwordx4 v132, s[36:37]
	s_waitcnt vmcnt(8)
	s_waitcnt lgkmcnt(0)
	s_barrier
	s_setprio 1
	v_mfma_f32_16x16x32_bf16 v[60:63], v[144:147], v[184:187], v[60:63]
	v_mfma_f32_16x16x32_bf16 v[56:59], v[160:163], v[184:187], v[56:59]
	v_mfma_f32_16x16x32_bf16 v[44:47], v[144:147], v[192:195], v[44:47]
	v_mfma_f32_16x16x32_bf16 v[40:43], v[160:163], v[192:195], v[40:43]
	v_mfma_f32_16x16x32_bf16 v[28:31], v[144:147], v[200:203], v[28:31]
	v_mfma_f32_16x16x32_bf16 v[24:27], v[160:163], v[200:203], v[24:27]
	v_mfma_f32_16x16x32_bf16 v[12:15], v[144:147], v[208:211], v[12:15]
	v_mfma_f32_16x16x32_bf16 v[8:11], v[160:163], v[208:211], v[8:11]
	v_mfma_f32_16x16x32_bf16 v[60:63], v[156:159], v[188:191], v[60:63]
	v_mfma_f32_16x16x32_bf16 v[56:59], v[164:167], v[188:191], v[56:59]
	v_mfma_f32_16x16x32_bf16 v[44:47], v[156:159], v[196:199], v[44:47]
	v_mfma_f32_16x16x32_bf16 v[40:43], v[164:167], v[196:199], v[40:43]
	v_mfma_f32_16x16x32_bf16 v[28:31], v[156:159], v[204:207], v[28:31]
	v_mfma_f32_16x16x32_bf16 v[24:27], v[164:167], v[204:207], v[24:27]
	v_mfma_f32_16x16x32_bf16 v[12:15], v[156:159], v[212:215], v[12:15]
	v_mfma_f32_16x16x32_bf16 v[8:11], v[164:167], v[212:215], v[8:11]
	v_mfma_f32_16x16x32_bf16 v[52:55], v[168:171], v[184:187], v[52:55]
	v_mfma_f32_16x16x32_bf16 v[48:51], v[176:179], v[184:187], v[48:51]
	v_mfma_f32_16x16x32_bf16 v[36:39], v[168:171], v[192:195], v[36:39]
	v_mfma_f32_16x16x32_bf16 v[32:35], v[176:179], v[192:195], v[32:35]
	v_mfma_f32_16x16x32_bf16 v[20:23], v[168:171], v[200:203], v[20:23]
	v_mfma_f32_16x16x32_bf16 v[16:19], v[176:179], v[200:203], v[16:19]
	v_mfma_f32_16x16x32_bf16 v[4:7], v[168:171], v[208:211], v[4:7]
	v_mfma_f32_16x16x32_bf16 v[0:3], v[176:179], v[208:211], v[0:3]
	v_mfma_f32_16x16x32_bf16 v[52:55], v[172:175], v[188:191], v[52:55]
	v_mfma_f32_16x16x32_bf16 v[48:51], v[180:183], v[188:191], v[48:51]
	v_mfma_f32_16x16x32_bf16 v[36:39], v[172:175], v[196:199], v[36:39]
	v_mfma_f32_16x16x32_bf16 v[32:35], v[180:183], v[196:199], v[32:35]
	v_mfma_f32_16x16x32_bf16 v[20:23], v[172:175], v[204:207], v[20:23]
	v_mfma_f32_16x16x32_bf16 v[16:19], v[180:183], v[204:207], v[16:19]
	v_mfma_f32_16x16x32_bf16 v[4:7], v[172:175], v[212:215], v[4:7]
	v_mfma_f32_16x16x32_bf16 v[0:3], v[180:183], v[212:215], v[0:3]
	s_setprio 0
	s_barrier
	s_add_i32 s60, 0, 0x18000
	v_add_u32_e32 v155, s60, v149
	s_add_i32 s61, 0, 0x1c000
	ds_read_b128 v[144:147], v155
	ds_read_b128 v[156:159], v155 offset:1024
	ds_read_b128 v[160:163], v155 offset:2048
	ds_read_b128 v[164:167], v155 offset:3072
	v_add_u32_e32 v155, s61, v149
	ds_read_b128 v[168:171], v155
	ds_read_b128 v[172:175], v155 offset:1024
	ds_read_b128 v[176:179], v155 offset:2048
	ds_read_b128 v[180:183], v155 offset:3072
	s_add_u32 s36, s36, 0x100000
	s_addc_u32 s37, s37, 0
	s_mov_b32 m0, s47
	ds_read_b128 v[184:187], v153 offset:32768
	ds_read_b128 v[188:191], v153 offset:33792
	ds_read_b128 v[192:195], v153 offset:34816
	ds_read_b128 v[196:199], v153 offset:35840
	ds_read_b128 v[200:203], v153 offset:36864
	ds_read_b128 v[204:207], v153 offset:37888
	ds_read_b128 v[208:211], v153 offset:38912
	ds_read_b128 v[212:215], v153 offset:39936
	global_load_lds_dwordx4 v128, s[36:37]
	s_mov_b32 m0, s48
	s_nop 0
	global_load_lds_dwordx4 v132, s[36:37]
	s_waitcnt vmcnt(8)
	s_waitcnt lgkmcnt(0)
	s_barrier
	s_setprio 1
	v_mfma_f32_16x16x32_bf16 v[124:127], v[144:147], v[184:187], v[124:127]
	v_mfma_f32_16x16x32_bf16 v[120:123], v[160:163], v[184:187], v[120:123]
	v_mfma_f32_16x16x32_bf16 v[108:111], v[144:147], v[192:195], v[108:111]
	v_mfma_f32_16x16x32_bf16 v[104:107], v[160:163], v[192:195], v[104:107]
	v_mfma_f32_16x16x32_bf16 v[92:95], v[144:147], v[200:203], v[92:95]
	v_mfma_f32_16x16x32_bf16 v[88:91], v[160:163], v[200:203], v[88:91]
	v_mfma_f32_16x16x32_bf16 v[76:79], v[144:147], v[208:211], v[76:79]
	v_mfma_f32_16x16x32_bf16 v[72:75], v[160:163], v[208:211], v[72:75]
	v_mfma_f32_16x16x32_bf16 v[124:127], v[156:159], v[188:191], v[124:127]
	v_mfma_f32_16x16x32_bf16 v[120:123], v[164:167], v[188:191], v[120:123]
	v_mfma_f32_16x16x32_bf16 v[108:111], v[156:159], v[196:199], v[108:111]
	v_mfma_f32_16x16x32_bf16 v[104:107], v[164:167], v[196:199], v[104:107]
	v_mfma_f32_16x16x32_bf16 v[92:95], v[156:159], v[204:207], v[92:95]
	v_mfma_f32_16x16x32_bf16 v[88:91], v[164:167], v[204:207], v[88:91]
	v_mfma_f32_16x16x32_bf16 v[76:79], v[156:159], v[212:215], v[76:79]
	v_mfma_f32_16x16x32_bf16 v[72:75], v[164:167], v[212:215], v[72:75]
	v_mfma_f32_16x16x32_bf16 v[116:119], v[168:171], v[184:187], v[116:119]
	v_mfma_f32_16x16x32_bf16 v[112:115], v[176:179], v[184:187], v[112:115]
	v_mfma_f32_16x16x32_bf16 v[100:103], v[168:171], v[192:195], v[100:103]
	v_mfma_f32_16x16x32_bf16 v[96:99], v[176:179], v[192:195], v[96:99]
	v_mfma_f32_16x16x32_bf16 v[84:87], v[168:171], v[200:203], v[84:87]
	v_mfma_f32_16x16x32_bf16 v[80:83], v[176:179], v[200:203], v[80:83]
	v_mfma_f32_16x16x32_bf16 v[68:71], v[168:171], v[208:211], v[68:71]
	v_mfma_f32_16x16x32_bf16 v[64:67], v[176:179], v[208:211], v[64:67]
	v_mfma_f32_16x16x32_bf16 v[116:119], v[172:175], v[188:191], v[116:119]
	v_mfma_f32_16x16x32_bf16 v[112:115], v[180:183], v[188:191], v[112:115]
	v_mfma_f32_16x16x32_bf16 v[100:103], v[172:175], v[196:199], v[100:103]
	v_mfma_f32_16x16x32_bf16 v[96:99], v[180:183], v[196:199], v[96:99]
	v_mfma_f32_16x16x32_bf16 v[84:87], v[172:175], v[204:207], v[84:87]
	v_mfma_f32_16x16x32_bf16 v[80:83], v[180:183], v[204:207], v[80:83]
	v_mfma_f32_16x16x32_bf16 v[68:71], v[172:175], v[212:215], v[68:71]
	v_mfma_f32_16x16x32_bf16 v[64:67], v[180:183], v[212:215], v[64:67]
	s_setprio 0
	s_barrier
	s_add_i32 s36, s60, s45
	s_mov_b32 m0, s36
	ds_read_b128 v[184:187], v153 offset:49152
	ds_read_b128 v[188:191], v153 offset:50176
	ds_read_b128 v[192:195], v153 offset:51200
	ds_read_b128 v[196:199], v153 offset:52224
	ds_read_b128 v[200:203], v153 offset:53248
	ds_read_b128 v[204:207], v153 offset:54272
	ds_read_b128 v[208:211], v153 offset:55296
	ds_read_b128 v[212:215], v153 offset:56320
	global_load_lds_dwordx4 v130, s[98:99]
	s_add_i32 m0, s36, 0x2000
	s_add_u32 s34, s34, 0x100080
	s_addc_u32 s35, s35, 0
	s_add_i32 s36, s61, s45
	global_load_lds_dwordx4 v134, s[98:99]
	s_mov_b32 m0, s36
	s_nop 0
	global_load_lds_dwordx4 v130, s[34:35]
	s_add_i32 m0, s36, 0x2000
	s_nop 0
	global_load_lds_dwordx4 v134, s[34:35]
	s_mov_b32 m0, s50
	s_nop 0
	global_load_lds_dwordx4 v128, s[100:101]
	s_mov_b32 m0, s51
	s_nop 0
	global_load_lds_dwordx4 v132, s[100:101]
	s_waitcnt vmcnt(8)
	s_waitcnt lgkmcnt(0)
	s_barrier
	s_setprio 1
	v_mfma_f32_16x16x32_bf16 v[60:63], v[144:147], v[184:187], v[60:63]
	v_mfma_f32_16x16x32_bf16 v[56:59], v[160:163], v[184:187], v[56:59]
	v_mfma_f32_16x16x32_bf16 v[44:47], v[144:147], v[192:195], v[44:47]
	v_mfma_f32_16x16x32_bf16 v[40:43], v[160:163], v[192:195], v[40:43]
	v_mfma_f32_16x16x32_bf16 v[28:31], v[144:147], v[200:203], v[28:31]
	v_mfma_f32_16x16x32_bf16 v[24:27], v[160:163], v[200:203], v[24:27]
	v_mfma_f32_16x16x32_bf16 v[12:15], v[144:147], v[208:211], v[12:15]
	v_mfma_f32_16x16x32_bf16 v[8:11], v[160:163], v[208:211], v[8:11]
	v_mfma_f32_16x16x32_bf16 v[60:63], v[156:159], v[188:191], v[60:63]
	v_mfma_f32_16x16x32_bf16 v[56:59], v[164:167], v[188:191], v[56:59]
	v_mfma_f32_16x16x32_bf16 v[44:47], v[156:159], v[196:199], v[44:47]
	v_mfma_f32_16x16x32_bf16 v[40:43], v[164:167], v[196:199], v[40:43]
	v_mfma_f32_16x16x32_bf16 v[28:31], v[156:159], v[204:207], v[28:31]
	v_mfma_f32_16x16x32_bf16 v[24:27], v[164:167], v[204:207], v[24:27]
	v_mfma_f32_16x16x32_bf16 v[12:15], v[156:159], v[212:215], v[12:15]
	v_mfma_f32_16x16x32_bf16 v[8:11], v[164:167], v[212:215], v[8:11]
	v_mfma_f32_16x16x32_bf16 v[52:55], v[168:171], v[184:187], v[52:55]
	v_mfma_f32_16x16x32_bf16 v[48:51], v[176:179], v[184:187], v[48:51]
	v_mfma_f32_16x16x32_bf16 v[36:39], v[168:171], v[192:195], v[36:39]
	v_mfma_f32_16x16x32_bf16 v[32:35], v[176:179], v[192:195], v[32:35]
	v_mfma_f32_16x16x32_bf16 v[20:23], v[168:171], v[200:203], v[20:23]
	v_mfma_f32_16x16x32_bf16 v[16:19], v[176:179], v[200:203], v[16:19]
	v_mfma_f32_16x16x32_bf16 v[4:7], v[168:171], v[208:211], v[4:7]
	v_mfma_f32_16x16x32_bf16 v[0:3], v[176:179], v[208:211], v[0:3]
	v_mfma_f32_16x16x32_bf16 v[52:55], v[172:175], v[188:191], v[52:55]
	v_mfma_f32_16x16x32_bf16 v[48:51], v[180:183], v[188:191], v[48:51]
	v_mfma_f32_16x16x32_bf16 v[36:39], v[172:175], v[196:199], v[36:39]
	v_mfma_f32_16x16x32_bf16 v[32:35], v[180:183], v[196:199], v[32:35]
	v_mfma_f32_16x16x32_bf16 v[20:23], v[172:175], v[204:207], v[20:23]
	v_mfma_f32_16x16x32_bf16 v[16:19], v[180:183], v[204:207], v[16:19]
	v_mfma_f32_16x16x32_bf16 v[4:7], v[172:175], v[212:215], v[4:7]
	v_mfma_f32_16x16x32_bf16 v[0:3], v[180:183], v[212:215], v[0:3]
	s_setprio 0
	s_barrier
	s_add_i32 s59, s59, 2
	s_add_u32 s57, s57, 0x100
	s_addc_u32 s58, s58, 0
	s_add_u32 s30, s30, 0x100
	s_addc_u32 s31, s31, 0
	s_cmp_gt_u32 s59, 61
	s_cbranch_scc0 .LBB0_1612
	s_and_b64 vcc, exec, s[20:21]
	s_cbranch_vccz .LBB0_1615
	s_barrier

.LBB0_1758:
	ds_read_b128 v[150:153], v147
	ds_read_b128 v[154:157], v147 offset:1024
	ds_read_b128 v[158:161], v147 offset:2048
	ds_read_b128 v[162:165], v147 offset:3072
	ds_read_b128 v[166:169], v148
	ds_read_b128 v[170:173], v148 offset:1024
	ds_read_b128 v[174:177], v148 offset:2048
	ds_read_b128 v[178:181], v148 offset:3072
	s_add_u32 s26, s24, 0xfff00080
	s_addc_u32 s27, s25, -1
	s_cmp_eq_u32 s55, 60
	s_cselect_b32 s29, s17, s27
	s_cselect_b32 s28, s51, s26
	s_cselect_b32 s27, s15, s54
	s_cselect_b32 s26, s52, s53
	s_add_i32 m0, s23, 0xc000
	ds_read_b128 v[182:185], v149
	ds_read_b128 v[186:189], v149 offset:1024
	ds_read_b128 v[190:193], v149 offset:2048
	ds_read_b128 v[194:197], v149 offset:3072
	ds_read_b128 v[198:201], v149 offset:4096
	ds_read_b128 v[202:205], v149 offset:5120
	ds_read_b128 v[206:209], v149 offset:6144
	ds_read_b128 v[210:213], v149 offset:7168
	global_load_lds_dwordx4 v138, s[24:25]
	s_add_i32 m0, s23, 0xe000
	s_nop 0
	global_load_lds_dwordx4 v136, s[24:25]
	s_waitcnt vmcnt(8)
	s_waitcnt lgkmcnt(0)
	s_barrier
	s_setprio 1
	v_mfma_f32_16x16x32_bf16 v[124:127], v[150:153], v[182:185], v[124:127]
	v_mfma_f32_16x16x32_bf16 v[120:123], v[158:161], v[182:185], v[120:123]
	v_mfma_f32_16x16x32_bf16 v[108:111], v[150:153], v[190:193], v[108:111]
	v_mfma_f32_16x16x32_bf16 v[104:107], v[158:161], v[190:193], v[104:107]
	v_mfma_f32_16x16x32_bf16 v[92:95], v[150:153], v[198:201], v[92:95]
	v_mfma_f32_16x16x32_bf16 v[88:91], v[158:161], v[198:201], v[88:91]
	v_mfma_f32_16x16x32_bf16 v[76:79], v[150:153], v[206:209], v[76:79]
	v_mfma_f32_16x16x32_bf16 v[72:75], v[158:161], v[206:209], v[72:75]
	v_mfma_f32_16x16x32_bf16 v[124:127], v[154:157], v[186:189], v[124:127]
	v_mfma_f32_16x16x32_bf16 v[120:123], v[162:165], v[186:189], v[120:123]
	v_mfma_f32_16x16x32_bf16 v[108:111], v[154:157], v[194:197], v[108:111]
	v_mfma_f32_16x16x32_bf16 v[104:107], v[162:165], v[194:197], v[104:107]
	v_mfma_f32_16x16x32_bf16 v[92:95], v[154:157], v[202:205], v[92:95]
	v_mfma_f32_16x16x32_bf16 v[88:91], v[162:165], v[202:205], v[88:91]
	v_mfma_f32_16x16x32_bf16 v[76:79], v[154:157], v[210:213], v[76:79]
	v_mfma_f32_16x16x32_bf16 v[72:75], v[162:165], v[210:213], v[72:75]
	v_mfma_f32_16x16x32_bf16 v[116:119], v[166:169], v[182:185], v[116:119]
	v_mfma_f32_16x16x32_bf16 v[112:115], v[174:177], v[182:185], v[112:115]
	v_mfma_f32_16x16x32_bf16 v[100:103], v[166:169], v[190:193], v[100:103]
	v_mfma_f32_16x16x32_bf16 v[96:99], v[174:177], v[190:193], v[96:99]
	v_mfma_f32_16x16x32_bf16 v[84:87], v[166:169], v[198:201], v[84:87]
	v_mfma_f32_16x16x32_bf16 v[80:83], v[174:177], v[198:201], v[80:83]
	v_mfma_f32_16x16x32_bf16 v[68:71], v[166:169], v[206:209], v[68:71]
	v_mfma_f32_16x16x32_bf16 v[64:67], v[174:177], v[206:209], v[64:67]
	v_mfma_f32_16x16x32_bf16 v[116:119], v[170:173], v[186:189], v[116:119]
	v_mfma_f32_16x16x32_bf16 v[112:115], v[178:181], v[186:189], v[112:115]
	v_mfma_f32_16x16x32_bf16 v[100:103], v[170:173], v[194:197], v[100:103]
	v_mfma_f32_16x16x32_bf16 v[96:99], v[178:181], v[194:197], v[96:99]
	v_mfma_f32_16x16x32_bf16 v[84:87], v[170:173], v[202:205], v[84:87]
	v_mfma_f32_16x16x32_bf16 v[80:83], v[178:181], v[202:205], v[80:83]
	v_mfma_f32_16x16x32_bf16 v[68:71], v[170:173], v[210:213], v[68:71]
	v_mfma_f32_16x16x32_bf16 v[64:67], v[178:181], v[210:213], v[64:67]
	s_setprio 0
	s_barrier
	s_add_u32 s98, s26, 0x80
	s_addc_u32 s99, s27, 0
	s_add_u32 s100, s28, 0x80
	s_addc_u32 s101, s29, 0
	s_add_i32 s56, s47, s39
	s_mov_b32 m0, s56
	ds_read_b128 v[182:185], v149 offset:16384
	ds_read_b128 v[186:189], v149 offset:17408
	ds_read_b128 v[190:193], v149 offset:18432
	ds_read_b128 v[194:197], v149 offset:19456
	ds_read_b128 v[198:201], v149 offset:20480
	ds_read_b128 v[202:205], v149 offset:21504
	ds_read_b128 v[206:209], v149 offset:22528
	ds_read_b128 v[210:213], v149 offset:23552
	global_load_lds_dwordx4 v132, s[26:27]
	s_add_i32 m0, s56, 0x2000
	s_add_u32 s56, s26, 0x100000
	s_addc_u32 s57, s27, 0
	s_add_i32 s58, s48, s39
	global_load_lds_dwordx4 v128, s[26:27]
	s_mov_b32 m0, s58
	s_nop 0
	global_load_lds_dwordx4 v132, s[56:57]
	s_add_i32 m0, s58, 0x2000
	s_nop 0
	global_load_lds_dwordx4 v128, s[56:57]
	s_mov_b32 m0, s23
	s_nop 0
	global_load_lds_dwordx4 v134, s[28:29]
	s_mov_b32 m0, s41
	s_nop 0
	global_load_lds_dwordx4 v130, s[28:29]
	s_waitcnt vmcnt(8)
	s_waitcnt lgkmcnt(0)
	s_barrier
	s_setprio 1
	v_mfma_f32_16x16x32_bf16 v[60:63], v[150:153], v[182:185], v[60:63]
	v_mfma_f32_16x16x32_bf16 v[56:59], v[158:161], v[182:185], v[56:59]
	v_mfma_f32_16x16x32_bf16 v[44:47], v[150:153], v[190:193], v[44:47]
	v_mfma_f32_16x16x32_bf16 v[40:43], v[158:161], v[190:193], v[40:43]
	v_mfma_f32_16x16x32_bf16 v[28:31], v[150:153], v[198:201], v[28:31]
	v_mfma_f32_16x16x32_bf16 v[24:27], v[158:161], v[198:201], v[24:27]
	v_mfma_f32_16x16x32_bf16 v[12:15], v[150:153], v[206:209], v[12:15]
	v_mfma_f32_16x16x32_bf16 v[8:11], v[158:161], v[206:209], v[8:11]
	v_mfma_f32_16x16x32_bf16 v[60:63], v[154:157], v[186:189], v[60:63]
	v_mfma_f32_16x16x32_bf16 v[56:59], v[162:165], v[186:189], v[56:59]
	v_mfma_f32_16x16x32_bf16 v[44:47], v[154:157], v[194:197], v[44:47]
	v_mfma_f32_16x16x32_bf16 v[40:43], v[162:165], v[194:197], v[40:43]
	v_mfma_f32_16x16x32_bf16 v[28:31], v[154:157], v[202:205], v[28:31]
	v_mfma_f32_16x16x32_bf16 v[24:27], v[162:165], v[202:205], v[24:27]
	v_mfma_f32_16x16x32_bf16 v[12:15], v[154:157], v[210:213], v[12:15]
	v_mfma_f32_16x16x32_bf16 v[8:11], v[162:165], v[210:213], v[8:11]
	v_mfma_f32_16x16x32_bf16 v[52:55], v[166:169], v[182:185], v[52:55]
	v_mfma_f32_16x16x32_bf16 v[48:51], v[174:177], v[182:185], v[48:51]
	v_mfma_f32_16x16x32_bf16 v[36:39], v[166:169], v[190:193], v[36:39]
	v_mfma_f32_16x16x32_bf16 v[32:35], v[174:177], v[190:193], v[32:35]
	v_mfma_f32_16x16x32_bf16 v[20:23], v[166:169], v[198:201], v[20:23]
	v_mfma_f32_16x16x32_bf16 v[16:19], v[174:177], v[198:201], v[16:19]
	v_mfma_f32_16x16x32_bf16 v[4:7], v[166:169], v[206:209], v[4:7]
	v_mfma_f32_16x16x32_bf16 v[0:3], v[174:177], v[206:209], v[0:3]
	v_mfma_f32_16x16x32_bf16 v[52:55], v[170:173], v[186:189], v[52:55]
	v_mfma_f32_16x16x32_bf16 v[48:51], v[178:181], v[186:189], v[48:51]
	v_mfma_f32_16x16x32_bf16 v[36:39], v[170:173], v[194:197], v[36:39]
	v_mfma_f32_16x16x32_bf16 v[32:35], v[178:181], v[194:197], v[32:35]
	v_mfma_f32_16x16x32_bf16 v[20:23], v[170:173], v[202:205], v[20:23]
	v_mfma_f32_16x16x32_bf16 v[16:19], v[178:181], v[202:205], v[16:19]
	v_mfma_f32_16x16x32_bf16 v[4:7], v[170:173], v[210:213], v[4:7]
	v_mfma_f32_16x16x32_bf16 v[0:3], v[178:181], v[210:213], v[0:3]
	s_setprio 0
	s_barrier
	s_add_i32 s56, 0, 0x18000
	s_add_i32 s57, 0, 0x1c000
	v_add_u32_e32 v162, s56, v145
	v_add_u32_e32 v178, s57, v145
	ds_read_b128 v[150:153], v162
	ds_read_b128 v[154:157], v162 offset:1024
	ds_read_b128 v[158:161], v162 offset:2048
	ds_read_b128 v[162:165], v162 offset:3072
	ds_read_b128 v[166:169], v178
	ds_read_b128 v[170:173], v178 offset:1024
	ds_read_b128 v[174:177], v178 offset:2048
	ds_read_b128 v[178:181], v178 offset:3072
	s_add_u32 s28, s28, 0x100000
	s_addc_u32 s29, s29, 0
	s_mov_b32 m0, s42
	ds_read_b128 v[182:185], v149 offset:32768
	ds_read_b128 v[186:189], v149 offset:33792
	ds_read_b128 v[190:193], v149 offset:34816
	ds_read_b128 v[194:197], v149 offset:35840
	ds_read_b128 v[198:201], v149 offset:36864
	ds_read_b128 v[202:205], v149 offset:37888
	ds_read_b128 v[206:209], v149 offset:38912
	ds_read_b128 v[210:213], v149 offset:39936
	global_load_lds_dwordx4 v134, s[28:29]
	s_mov_b32 m0, s43
	s_nop 0
	global_load_lds_dwordx4 v130, s[28:29]
	s_waitcnt vmcnt(8)
	s_waitcnt lgkmcnt(0)
	s_barrier
	s_setprio 1
	v_mfma_f32_16x16x32_bf16 v[124:127], v[150:153], v[182:185], v[124:127]
	v_mfma_f32_16x16x32_bf16 v[120:123], v[158:161], v[182:185], v[120:123]
	v_mfma_f32_16x16x32_bf16 v[108:111], v[150:153], v[190:193], v[108:111]
	v_mfma_f32_16x16x32_bf16 v[104:107], v[158:161], v[190:193], v[104:107]
	v_mfma_f32_16x16x32_bf16 v[92:95], v[150:153], v[198:201], v[92:95]
	v_mfma_f32_16x16x32_bf16 v[88:91], v[158:161], v[198:201], v[88:91]
	v_mfma_f32_16x16x32_bf16 v[76:79], v[150:153], v[206:209], v[76:79]
	v_mfma_f32_16x16x32_bf16 v[72:75], v[158:161], v[206:209], v[72:75]
	v_mfma_f32_16x16x32_bf16 v[124:127], v[154:157], v[186:189], v[124:127]
	v_mfma_f32_16x16x32_bf16 v[120:123], v[162:165], v[186:189], v[120:123]
	v_mfma_f32_16x16x32_bf16 v[108:111], v[154:157], v[194:197], v[108:111]
	v_mfma_f32_16x16x32_bf16 v[104:107], v[162:165], v[194:197], v[104:107]
	v_mfma_f32_16x16x32_bf16 v[92:95], v[154:157], v[202:205], v[92:95]
	v_mfma_f32_16x16x32_bf16 v[88:91], v[162:165], v[202:205], v[88:91]
	v_mfma_f32_16x16x32_bf16 v[76:79], v[154:157], v[210:213], v[76:79]
	v_mfma_f32_16x16x32_bf16 v[72:75], v[162:165], v[210:213], v[72:75]
	v_mfma_f32_16x16x32_bf16 v[116:119], v[166:169], v[182:185], v[116:119]
	v_mfma_f32_16x16x32_bf16 v[112:115], v[174:177], v[182:185], v[112:115]
	v_mfma_f32_16x16x32_bf16 v[100:103], v[166:169], v[190:193], v[100:103]
	v_mfma_f32_16x16x32_bf16 v[96:99], v[174:177], v[190:193], v[96:99]
	v_mfma_f32_16x16x32_bf16 v[84:87], v[166:169], v[198:201], v[84:87]
	v_mfma_f32_16x16x32_bf16 v[80:83], v[174:177], v[198:201], v[80:83]
	v_mfma_f32_16x16x32_bf16 v[68:71], v[166:169], v[206:209], v[68:71]
	v_mfma_f32_16x16x32_bf16 v[64:67], v[174:177], v[206:209], v[64:67]
	v_mfma_f32_16x16x32_bf16 v[116:119], v[170:173], v[186:189], v[116:119]
	v_mfma_f32_16x16x32_bf16 v[112:115], v[178:181], v[186:189], v[112:115]
	v_mfma_f32_16x16x32_bf16 v[100:103], v[170:173], v[194:197], v[100:103]
	v_mfma_f32_16x16x32_bf16 v[96:99], v[178:181], v[194:197], v[96:99]
	v_mfma_f32_16x16x32_bf16 v[84:87], v[170:173], v[202:205], v[84:87]
	v_mfma_f32_16x16x32_bf16 v[80:83], v[178:181], v[202:205], v[80:83]
	v_mfma_f32_16x16x32_bf16 v[68:71], v[170:173], v[210:213], v[68:71]
	v_mfma_f32_16x16x32_bf16 v[64:67], v[178:181], v[210:213], v[64:67]
	s_setprio 0
	s_barrier
	s_add_i32 s28, s56, s39
	s_mov_b32 m0, s28
	ds_read_b128 v[182:185], v149 offset:49152
	ds_read_b128 v[186:189], v149 offset:50176
	ds_read_b128 v[190:193], v149 offset:51200
	ds_read_b128 v[194:197], v149 offset:52224
	ds_read_b128 v[198:201], v149 offset:53248
	ds_read_b128 v[202:205], v149 offset:54272
	ds_read_b128 v[206:209], v149 offset:55296
	ds_read_b128 v[210:213], v149 offset:56320
	global_load_lds_dwordx4 v132, s[98:99]
	s_add_i32 m0, s28, 0x2000
	s_add_u32 s26, s26, 0x100080
	s_addc_u32 s27, s27, 0
	s_add_i32 s28, s57, s39
	global_load_lds_dwordx4 v128, s[98:99]
	s_mov_b32 m0, s28
	s_nop 0
	global_load_lds_dwordx4 v132, s[26:27]
	s_add_i32 m0, s28, 0x2000
	s_nop 0
	global_load_lds_dwordx4 v128, s[26:27]
	s_mov_b32 m0, s44
	s_nop 0
	global_load_lds_dwordx4 v134, s[100:101]
	s_mov_b32 m0, s45
	s_nop 0
	global_load_lds_dwordx4 v130, s[100:101]
	s_waitcnt vmcnt(8)
	s_waitcnt lgkmcnt(0)
	s_barrier
	s_setprio 1
	v_mfma_f32_16x16x32_bf16 v[60:63], v[150:153], v[182:185], v[60:63]
	v_mfma_f32_16x16x32_bf16 v[56:59], v[158:161], v[182:185], v[56:59]
	v_mfma_f32_16x16x32_bf16 v[44:47], v[150:153], v[190:193], v[44:47]
	v_mfma_f32_16x16x32_bf16 v[40:43], v[158:161], v[190:193], v[40:43]
	v_mfma_f32_16x16x32_bf16 v[28:31], v[150:153], v[198:201], v[28:31]
	v_mfma_f32_16x16x32_bf16 v[24:27], v[158:161], v[198:201], v[24:27]
	v_mfma_f32_16x16x32_bf16 v[12:15], v[150:153], v[206:209], v[12:15]
	v_mfma_f32_16x16x32_bf16 v[8:11], v[158:161], v[206:209], v[8:11]
	v_mfma_f32_16x16x32_bf16 v[60:63], v[154:157], v[186:189], v[60:63]
	v_mfma_f32_16x16x32_bf16 v[56:59], v[162:165], v[186:189], v[56:59]
	v_mfma_f32_16x16x32_bf16 v[44:47], v[154:157], v[194:197], v[44:47]
	v_mfma_f32_16x16x32_bf16 v[40:43], v[162:165], v[194:197], v[40:43]
	v_mfma_f32_16x16x32_bf16 v[28:31], v[154:157], v[202:205], v[28:31]
	v_mfma_f32_16x16x32_bf16 v[24:27], v[162:165], v[202:205], v[24:27]
	v_mfma_f32_16x16x32_bf16 v[12:15], v[154:157], v[210:213], v[12:15]
	v_mfma_f32_16x16x32_bf16 v[8:11], v[162:165], v[210:213], v[8:11]
	v_mfma_f32_16x16x32_bf16 v[52:55], v[166:169], v[182:185], v[52:55]
	v_mfma_f32_16x16x32_bf16 v[48:51], v[174:177], v[182:185], v[48:51]
	v_mfma_f32_16x16x32_bf16 v[36:39], v[166:169], v[190:193], v[36:39]
	v_mfma_f32_16x16x32_bf16 v[32:35], v[174:177], v[190:193], v[32:35]
	v_mfma_f32_16x16x32_bf16 v[20:23], v[166:169], v[198:201], v[20:23]
	v_mfma_f32_16x16x32_bf16 v[16:19], v[174:177], v[198:201], v[16:19]
	v_mfma_f32_16x16x32_bf16 v[4:7], v[166:169], v[206:209], v[4:7]
	v_mfma_f32_16x16x32_bf16 v[0:3], v[174:177], v[206:209], v[0:3]
	v_mfma_f32_16x16x32_bf16 v[52:55], v[170:173], v[186:189], v[52:55]
	v_mfma_f32_16x16x32_bf16 v[48:51], v[178:181], v[186:189], v[48:51]
	v_mfma_f32_16x16x32_bf16 v[36:39], v[170:173], v[194:197], v[36:39]
	v_mfma_f32_16x16x32_bf16 v[32:35], v[178:181], v[194:197], v[32:35]
	v_mfma_f32_16x16x32_bf16 v[20:23], v[170:173], v[202:205], v[20:23]
	v_mfma_f32_16x16x32_bf16 v[16:19], v[178:181], v[202:205], v[16:19]
	v_mfma_f32_16x16x32_bf16 v[4:7], v[170:173], v[210:213], v[4:7]
	v_mfma_f32_16x16x32_bf16 v[0:3], v[178:181], v[210:213], v[0:3]
	s_setprio 0
	s_barrier
	s_add_i32 s55, s55, 2
	s_add_u32 s53, s53, 0x100
	s_addc_u32 s54, s54, 0
	s_add_u32 s24, s24, 0x100
	s_addc_u32 s25, s25, 0
	s_cmp_gt_u32 s55, 61
	s_cbranch_scc0 .LBB0_1758
	s_and_b64 vcc, exec, s[12:13]
	s_cbranch_vccz .LBB0_1761
	s_barrier

.LBB0_1963:
	ds_read_b128 v[144:147], v151
	ds_read_b128 v[156:159], v151 offset:1024
	ds_read_b128 v[160:163], v151 offset:2048
	ds_read_b128 v[164:167], v151 offset:3072
	ds_read_b128 v[168:171], v152
	ds_read_b128 v[172:175], v152 offset:1024
	ds_read_b128 v[176:179], v152 offset:2048
	ds_read_b128 v[180:183], v152 offset:3072
	s_add_u32 s28, s26, 0x100
	s_addc_u32 s29, s27, 0
	s_cmpk_eq_i32 s59, 0xa8
	s_cselect_b32 s35, s7, s29
	s_cselect_b32 s34, s6, s28
	s_cselect_b32 s31, s25, s58
	s_cselect_b32 s30, s24, s57
	s_add_i32 m0, s43, 0xc000
	ds_read_b128 v[184:187], v153
	ds_read_b128 v[188:191], v153 offset:1024
	ds_read_b128 v[192:195], v153 offset:2048
	ds_read_b128 v[196:199], v153 offset:3072
	ds_read_b128 v[200:203], v153 offset:4096
	ds_read_b128 v[204:207], v153 offset:5120
	ds_read_b128 v[208:211], v153 offset:6144
	ds_read_b128 v[212:215], v153 offset:7168
	global_load_lds_dwordx4 v138, s[26:27]
	s_add_i32 m0, s43, 0xe000
	s_nop 0
	global_load_lds_dwordx4 v136, s[26:27]
	s_waitcnt vmcnt(8)
	s_waitcnt lgkmcnt(0)
	s_barrier
	s_setprio 1
	v_mfma_f32_16x16x32_bf16 v[124:127], v[144:147], v[184:187], v[124:127]
	v_mfma_f32_16x16x32_bf16 v[120:123], v[160:163], v[184:187], v[120:123]
	v_mfma_f32_16x16x32_bf16 v[108:111], v[144:147], v[192:195], v[108:111]
	v_mfma_f32_16x16x32_bf16 v[104:107], v[160:163], v[192:195], v[104:107]
	v_mfma_f32_16x16x32_bf16 v[92:95], v[144:147], v[200:203], v[92:95]
	v_mfma_f32_16x16x32_bf16 v[88:91], v[160:163], v[200:203], v[88:91]
	v_mfma_f32_16x16x32_bf16 v[76:79], v[144:147], v[208:211], v[76:79]
	v_mfma_f32_16x16x32_bf16 v[72:75], v[160:163], v[208:211], v[72:75]
	v_mfma_f32_16x16x32_bf16 v[124:127], v[156:159], v[188:191], v[124:127]
	v_mfma_f32_16x16x32_bf16 v[120:123], v[164:167], v[188:191], v[120:123]
	v_mfma_f32_16x16x32_bf16 v[108:111], v[156:159], v[196:199], v[108:111]
	v_mfma_f32_16x16x32_bf16 v[104:107], v[164:167], v[196:199], v[104:107]
	v_mfma_f32_16x16x32_bf16 v[92:95], v[156:159], v[204:207], v[92:95]
	v_mfma_f32_16x16x32_bf16 v[88:91], v[164:167], v[204:207], v[88:91]
	v_mfma_f32_16x16x32_bf16 v[76:79], v[156:159], v[212:215], v[76:79]
	v_mfma_f32_16x16x32_bf16 v[72:75], v[164:167], v[212:215], v[72:75]
	v_mfma_f32_16x16x32_bf16 v[116:119], v[168:171], v[184:187], v[116:119]
	v_mfma_f32_16x16x32_bf16 v[112:115], v[176:179], v[184:187], v[112:115]
	v_mfma_f32_16x16x32_bf16 v[100:103], v[168:171], v[192:195], v[100:103]
	v_mfma_f32_16x16x32_bf16 v[96:99], v[176:179], v[192:195], v[96:99]
	v_mfma_f32_16x16x32_bf16 v[84:87], v[168:171], v[200:203], v[84:87]
	v_mfma_f32_16x16x32_bf16 v[80:83], v[176:179], v[200:203], v[80:83]
	v_mfma_f32_16x16x32_bf16 v[68:71], v[168:171], v[208:211], v[68:71]
	v_mfma_f32_16x16x32_bf16 v[64:67], v[176:179], v[208:211], v[64:67]
	v_mfma_f32_16x16x32_bf16 v[116:119], v[172:175], v[188:191], v[116:119]
	v_mfma_f32_16x16x32_bf16 v[112:115], v[180:183], v[188:191], v[112:115]
	v_mfma_f32_16x16x32_bf16 v[100:103], v[172:175], v[196:199], v[100:103]
	v_mfma_f32_16x16x32_bf16 v[96:99], v[180:183], v[196:199], v[96:99]
	v_mfma_f32_16x16x32_bf16 v[84:87], v[172:175], v[204:207], v[84:87]
	v_mfma_f32_16x16x32_bf16 v[80:83], v[180:183], v[204:207], v[80:83]
	v_mfma_f32_16x16x32_bf16 v[68:71], v[172:175], v[212:215], v[68:71]
	v_mfma_f32_16x16x32_bf16 v[64:67], v[180:183], v[212:215], v[64:67]
	s_setprio 0
	s_barrier
	s_add_u32 s98, s30, 0x80
	s_addc_u32 s99, s31, 0
	s_add_u32 s100, s34, 0x80
	s_addc_u32 s101, s35, 0
	s_add_i32 s26, s52, s42
	s_mov_b32 m0, s26
	ds_read_b128 v[184:187], v153 offset:16384
	ds_read_b128 v[188:191], v153 offset:17408
	ds_read_b128 v[192:195], v153 offset:18432
	ds_read_b128 v[196:199], v153 offset:19456
	ds_read_b128 v[200:203], v153 offset:20480
	ds_read_b128 v[204:207], v153 offset:21504
	ds_read_b128 v[208:211], v153 offset:22528
	ds_read_b128 v[212:215], v153 offset:23552
	global_load_lds_dwordx4 v130, s[30:31]
	s_add_i32 m0, s26, 0x2000
	s_add_u32 s26, s30, 0x2b0000
	s_addc_u32 s27, s31, 0
	s_add_i32 s60, s53, s42
	global_load_lds_dwordx4 v134, s[30:31]
	s_mov_b32 m0, s60
	s_nop 0
	global_load_lds_dwordx4 v130, s[26:27]
	s_add_i32 m0, s60, 0x2000
	s_nop 0
	global_load_lds_dwordx4 v134, s[26:27]
	s_mov_b32 m0, s43
	s_nop 0
	global_load_lds_dwordx4 v128, s[34:35]
	s_mov_b32 m0, s44
	s_nop 0
	global_load_lds_dwordx4 v132, s[34:35]
	s_waitcnt vmcnt(8)
	s_waitcnt lgkmcnt(0)
	s_barrier
	s_setprio 1
	v_mfma_f32_16x16x32_bf16 v[60:63], v[144:147], v[184:187], v[60:63]
	v_mfma_f32_16x16x32_bf16 v[56:59], v[160:163], v[184:187], v[56:59]
	v_mfma_f32_16x16x32_bf16 v[44:47], v[144:147], v[192:195], v[44:47]
	v_mfma_f32_16x16x32_bf16 v[40:43], v[160:163], v[192:195], v[40:43]
	v_mfma_f32_16x16x32_bf16 v[28:31], v[144:147], v[200:203], v[28:31]
	v_mfma_f32_16x16x32_bf16 v[24:27], v[160:163], v[200:203], v[24:27]
	v_mfma_f32_16x16x32_bf16 v[12:15], v[144:147], v[208:211], v[12:15]
	v_mfma_f32_16x16x32_bf16 v[8:11], v[160:163], v[208:211], v[8:11]
	v_mfma_f32_16x16x32_bf16 v[60:63], v[156:159], v[188:191], v[60:63]
	v_mfma_f32_16x16x32_bf16 v[56:59], v[164:167], v[188:191], v[56:59]
	v_mfma_f32_16x16x32_bf16 v[44:47], v[156:159], v[196:199], v[44:47]
	v_mfma_f32_16x16x32_bf16 v[40:43], v[164:167], v[196:199], v[40:43]
	v_mfma_f32_16x16x32_bf16 v[28:31], v[156:159], v[204:207], v[28:31]
	v_mfma_f32_16x16x32_bf16 v[24:27], v[164:167], v[204:207], v[24:27]
	v_mfma_f32_16x16x32_bf16 v[12:15], v[156:159], v[212:215], v[12:15]
	v_mfma_f32_16x16x32_bf16 v[8:11], v[164:167], v[212:215], v[8:11]
	v_mfma_f32_16x16x32_bf16 v[52:55], v[168:171], v[184:187], v[52:55]
	v_mfma_f32_16x16x32_bf16 v[48:51], v[176:179], v[184:187], v[48:51]
	v_mfma_f32_16x16x32_bf16 v[36:39], v[168:171], v[192:195], v[36:39]
	v_mfma_f32_16x16x32_bf16 v[32:35], v[176:179], v[192:195], v[32:35]
	v_mfma_f32_16x16x32_bf16 v[20:23], v[168:171], v[200:203], v[20:23]
	v_mfma_f32_16x16x32_bf16 v[16:19], v[176:179], v[200:203], v[16:19]
	v_mfma_f32_16x16x32_bf16 v[4:7], v[168:171], v[208:211], v[4:7]
	v_mfma_f32_16x16x32_bf16 v[0:3], v[176:179], v[208:211], v[0:3]
	v_mfma_f32_16x16x32_bf16 v[52:55], v[172:175], v[188:191], v[52:55]
	v_mfma_f32_16x16x32_bf16 v[48:51], v[180:183], v[188:191], v[48:51]
	v_mfma_f32_16x16x32_bf16 v[36:39], v[172:175], v[196:199], v[36:39]
	v_mfma_f32_16x16x32_bf16 v[32:35], v[180:183], v[196:199], v[32:35]
	v_mfma_f32_16x16x32_bf16 v[20:23], v[172:175], v[204:207], v[20:23]
	v_mfma_f32_16x16x32_bf16 v[16:19], v[180:183], v[204:207], v[16:19]
	v_mfma_f32_16x16x32_bf16 v[4:7], v[172:175], v[212:215], v[4:7]
	v_mfma_f32_16x16x32_bf16 v[0:3], v[180:183], v[212:215], v[0:3]
	s_setprio 0
	s_barrier
	s_add_i32 s60, 0, 0x18000
	v_add_u32_e32 v155, s60, v149
	s_add_i32 s61, 0, 0x1c000
	ds_read_b128 v[144:147], v155
	ds_read_b128 v[156:159], v155 offset:1024
	ds_read_b128 v[160:163], v155 offset:2048
	ds_read_b128 v[164:167], v155 offset:3072
	v_add_u32_e32 v155, s61, v149
	ds_read_b128 v[168:171], v155
	ds_read_b128 v[172:175], v155 offset:1024
	ds_read_b128 v[176:179], v155 offset:2048
	ds_read_b128 v[180:183], v155 offset:3072
	s_add_u32 s26, s34, 0x2b0000
	s_addc_u32 s27, s35, 0
	s_mov_b32 m0, s45
	ds_read_b128 v[184:187], v153 offset:32768
	ds_read_b128 v[188:191], v153 offset:33792
	ds_read_b128 v[192:195], v153 offset:34816
	ds_read_b128 v[196:199], v153 offset:35840
	ds_read_b128 v[200:203], v153 offset:36864
	ds_read_b128 v[204:207], v153 offset:37888
	ds_read_b128 v[208:211], v153 offset:38912
	ds_read_b128 v[212:215], v153 offset:39936
	global_load_lds_dwordx4 v128, s[26:27]
	s_mov_b32 m0, s46
	s_nop 0
	global_load_lds_dwordx4 v132, s[26:27]
	s_waitcnt vmcnt(8)
	s_waitcnt lgkmcnt(0)
	s_barrier
	s_setprio 1
	v_mfma_f32_16x16x32_bf16 v[124:127], v[144:147], v[184:187], v[124:127]
	v_mfma_f32_16x16x32_bf16 v[120:123], v[160:163], v[184:187], v[120:123]
	v_mfma_f32_16x16x32_bf16 v[108:111], v[144:147], v[192:195], v[108:111]
	v_mfma_f32_16x16x32_bf16 v[104:107], v[160:163], v[192:195], v[104:107]
	v_mfma_f32_16x16x32_bf16 v[92:95], v[144:147], v[200:203], v[92:95]
	v_mfma_f32_16x16x32_bf16 v[88:91], v[160:163], v[200:203], v[88:91]
	v_mfma_f32_16x16x32_bf16 v[76:79], v[144:147], v[208:211], v[76:79]
	v_mfma_f32_16x16x32_bf16 v[72:75], v[160:163], v[208:211], v[72:75]
	v_mfma_f32_16x16x32_bf16 v[124:127], v[156:159], v[188:191], v[124:127]
	v_mfma_f32_16x16x32_bf16 v[120:123], v[164:167], v[188:191], v[120:123]
	v_mfma_f32_16x16x32_bf16 v[108:111], v[156:159], v[196:199], v[108:111]
	v_mfma_f32_16x16x32_bf16 v[104:107], v[164:167], v[196:199], v[104:107]
	v_mfma_f32_16x16x32_bf16 v[92:95], v[156:159], v[204:207], v[92:95]
	v_mfma_f32_16x16x32_bf16 v[88:91], v[164:167], v[204:207], v[88:91]
	v_mfma_f32_16x16x32_bf16 v[76:79], v[156:159], v[212:215], v[76:79]
	v_mfma_f32_16x16x32_bf16 v[72:75], v[164:167], v[212:215], v[72:75]
	v_mfma_f32_16x16x32_bf16 v[116:119], v[168:171], v[184:187], v[116:119]
	v_mfma_f32_16x16x32_bf16 v[112:115], v[176:179], v[184:187], v[112:115]
	v_mfma_f32_16x16x32_bf16 v[100:103], v[168:171], v[192:195], v[100:103]
	v_mfma_f32_16x16x32_bf16 v[96:99], v[176:179], v[192:195], v[96:99]
	v_mfma_f32_16x16x32_bf16 v[84:87], v[168:171], v[200:203], v[84:87]
	v_mfma_f32_16x16x32_bf16 v[80:83], v[176:179], v[200:203], v[80:83]
	v_mfma_f32_16x16x32_bf16 v[68:71], v[168:171], v[208:211], v[68:71]
	v_mfma_f32_16x16x32_bf16 v[64:67], v[176:179], v[208:211], v[64:67]
	v_mfma_f32_16x16x32_bf16 v[116:119], v[172:175], v[188:191], v[116:119]
	v_mfma_f32_16x16x32_bf16 v[112:115], v[180:183], v[188:191], v[112:115]
	v_mfma_f32_16x16x32_bf16 v[100:103], v[172:175], v[196:199], v[100:103]
	v_mfma_f32_16x16x32_bf16 v[96:99], v[180:183], v[196:199], v[96:99]
	v_mfma_f32_16x16x32_bf16 v[84:87], v[172:175], v[204:207], v[84:87]
	v_mfma_f32_16x16x32_bf16 v[80:83], v[180:183], v[204:207], v[80:83]
	v_mfma_f32_16x16x32_bf16 v[68:71], v[172:175], v[212:215], v[68:71]
	v_mfma_f32_16x16x32_bf16 v[64:67], v[180:183], v[212:215], v[64:67]
	s_setprio 0
	s_barrier
	s_add_i32 s26, s60, s42
	s_mov_b32 m0, s26
	ds_read_b128 v[184:187], v153 offset:49152
	ds_read_b128 v[188:191], v153 offset:50176
	ds_read_b128 v[192:195], v153 offset:51200
	ds_read_b128 v[196:199], v153 offset:52224
	ds_read_b128 v[200:203], v153 offset:53248
	ds_read_b128 v[204:207], v153 offset:54272
	ds_read_b128 v[208:211], v153 offset:55296
	ds_read_b128 v[212:215], v153 offset:56320
	global_load_lds_dwordx4 v130, s[98:99]
	s_add_i32 m0, s26, 0x2000
	s_add_u32 s26, s30, 0x2b0080
	s_addc_u32 s27, s31, 0
	s_add_i32 s30, s61, s42
	global_load_lds_dwordx4 v134, s[98:99]
	s_mov_b32 m0, s30
	s_nop 0
	global_load_lds_dwordx4 v130, s[26:27]
	s_add_i32 m0, s30, 0x2000
	s_nop 0
	global_load_lds_dwordx4 v134, s[26:27]
	s_mov_b32 m0, s50
	s_nop 0
	global_load_lds_dwordx4 v128, s[100:101]
	s_mov_b32 m0, s51
	s_nop 0
	global_load_lds_dwordx4 v132, s[100:101]
	s_waitcnt vmcnt(8)
	s_waitcnt lgkmcnt(0)
	s_barrier
	s_setprio 1
	v_mfma_f32_16x16x32_bf16 v[60:63], v[144:147], v[184:187], v[60:63]
	v_mfma_f32_16x16x32_bf16 v[56:59], v[160:163], v[184:187], v[56:59]
	v_mfma_f32_16x16x32_bf16 v[44:47], v[144:147], v[192:195], v[44:47]
	v_mfma_f32_16x16x32_bf16 v[40:43], v[160:163], v[192:195], v[40:43]
	v_mfma_f32_16x16x32_bf16 v[28:31], v[144:147], v[200:203], v[28:31]
	v_mfma_f32_16x16x32_bf16 v[24:27], v[160:163], v[200:203], v[24:27]
	v_mfma_f32_16x16x32_bf16 v[12:15], v[144:147], v[208:211], v[12:15]
	v_mfma_f32_16x16x32_bf16 v[8:11], v[160:163], v[208:211], v[8:11]
	v_mfma_f32_16x16x32_bf16 v[60:63], v[156:159], v[188:191], v[60:63]
	v_mfma_f32_16x16x32_bf16 v[56:59], v[164:167], v[188:191], v[56:59]
	v_mfma_f32_16x16x32_bf16 v[44:47], v[156:159], v[196:199], v[44:47]
	v_mfma_f32_16x16x32_bf16 v[40:43], v[164:167], v[196:199], v[40:43]
	v_mfma_f32_16x16x32_bf16 v[28:31], v[156:159], v[204:207], v[28:31]
	v_mfma_f32_16x16x32_bf16 v[24:27], v[164:167], v[204:207], v[24:27]
	v_mfma_f32_16x16x32_bf16 v[12:15], v[156:159], v[212:215], v[12:15]
	v_mfma_f32_16x16x32_bf16 v[8:11], v[164:167], v[212:215], v[8:11]
	v_mfma_f32_16x16x32_bf16 v[52:55], v[168:171], v[184:187], v[52:55]
	v_mfma_f32_16x16x32_bf16 v[48:51], v[176:179], v[184:187], v[48:51]
	v_mfma_f32_16x16x32_bf16 v[36:39], v[168:171], v[192:195], v[36:39]
	v_mfma_f32_16x16x32_bf16 v[32:35], v[176:179], v[192:195], v[32:35]
	v_mfma_f32_16x16x32_bf16 v[20:23], v[168:171], v[200:203], v[20:23]
	v_mfma_f32_16x16x32_bf16 v[16:19], v[176:179], v[200:203], v[16:19]
	v_mfma_f32_16x16x32_bf16 v[4:7], v[168:171], v[208:211], v[4:7]
	v_mfma_f32_16x16x32_bf16 v[0:3], v[176:179], v[208:211], v[0:3]
	v_mfma_f32_16x16x32_bf16 v[52:55], v[172:175], v[188:191], v[52:55]
	v_mfma_f32_16x16x32_bf16 v[48:51], v[180:183], v[188:191], v[48:51]
	v_mfma_f32_16x16x32_bf16 v[36:39], v[172:175], v[196:199], v[36:39]
	v_mfma_f32_16x16x32_bf16 v[32:35], v[180:183], v[196:199], v[32:35]
	v_mfma_f32_16x16x32_bf16 v[20:23], v[172:175], v[204:207], v[20:23]
	v_mfma_f32_16x16x32_bf16 v[16:19], v[180:183], v[204:207], v[16:19]
	v_mfma_f32_16x16x32_bf16 v[4:7], v[172:175], v[212:215], v[4:7]
	v_mfma_f32_16x16x32_bf16 v[0:3], v[180:183], v[212:215], v[0:3]
	s_setprio 0
	s_barrier
	s_add_i32 s59, s59, 2
	s_add_u32 s57, s57, 0x100
	s_addc_u32 s58, s58, 0
	s_cmpk_gt_u32 s59, 0xa9
	s_mov_b64 s[26:27], s[28:29]
	s_cbranch_scc0 .LBB0_1963
	s_and_b64 vcc, exec, s[22:23]
	s_cbranch_vccz .LBB0_1966
	s_barrier
